# v11 plus non-temporal hint on the f32 K/V cache-row output stores of the input-projection epilogue
# baseline (speedup 1.0000x reference)
; __device__ __forceinline__ u32x2 pk4(f32x4 v) { u32x2 w; w.x = pk2(v[0], v[1]); w.y = pk2(v[2], v[3]); return w; }
;     __device__ __forceinline__ void operator()(const f32x4 (&acc)[2][2][4][2], const Unit& u, int wr, int wc, int fr, int fq) const {
;     ...
;             const bool isv = pn >= 8; bf16_t* KV = isv ? VA : KA; float* op = isv ? avp : akp; float* os = isv ? avs : aks;
;             const int c0 = (pn - (isv ? 8 : 4)) * 256 + lc0;
;             if (pm < 128) {
;                 const int b1 = (pm >> 4) + 1;
; #pragma unroll
;                 for (int ai = 0; ai < 2; ++ai)
; #pragma unroll
;                     for (int m = 0; m < 4; ++m) { const int r = pm * 256 + ai * 128 + m * 16 + lr0;
;                         bf16_t* kp = KV + (size_t)(r + 64 * b1) * 1024 + c0; float* fp = op + (size_t)(r + 16 * b1) * 1024 + c0;
; #pragma unroll
;                         for (int bj = 0; bj < 2; ++bj)
; #pragma unroll
;                             for (int n = 0; n < 2; ++n) { const f32x4 v = acc[ai][bj][m][n]; *(u32x2*)(kp + bj * 128 + n * 16) = pk4(v); *(f32x4*)(fp + bj * 128 + n * 16) = v; } }
;             } else {
; #pragma unroll
;                 for (int m = 0; m < 4; ++m) { const int lr = m * 16 + lr0;
;                     bf16_t* kp = KV + (size_t)(KS0 + (m + 4 * wr) * KSR + 1088 + fr) * 1024 + c0; float* fp = os + (size_t)lr * 1024 + c0;
; #pragma unroll
;                     for (int bj = 0; bj < 2; ++bj)
; #pragma unroll
;                         for (int n = 0; n < 2; ++n) { const f32x4 v = acc[0][bj][m][n]; *(u32x2*)(kp + bj * 128 + n * 16) = pk4(v); *(f32x4*)(fp + bj * 128 + n * 16) = v; } }
;                 if (wr == 0) {
;                     { bf16_t* kp = KV + (size_t)(MT + fr) * 1024 + c0;
; #pragma unroll
;                       for (int bj = 0; bj < 2; ++bj)
; #pragma unroll
;                           for (int n = 0; n < 2; ++n) *(u32x2*)(kp + bj * 128 + n * 16) = pk4(acc[1][bj][0][n]); }
; #pragma unroll 1
;                     for (int bb = 0; bb < 8; ++bb) { float* fp = op + (size_t)(bb * 4112 + fr) * 1024 + c0;
; #pragma unroll
;                         for (int bj = 0; bj < 2; ++bj)
; #pragma unroll
;                             for (int n = 0; n < 2; ++n) *(f32x4*)(fp + bj * 128 + n * 16) = acc[1][bj][0][n]; }
;                 }
.LBB0_217:
	s_andn2_b64 vcc, exec, s[0:1]
	s_cbranch_vccnz .LBB0_225
	s_cmp_gt_u32 s59, 7
	s_cselect_b64 s[16:17], -1, 0
	s_and_b64 s[0:1], s[16:17], exec
	s_cselect_b32 s0, 0x1e3a0000, s90
	s_add_u32 s0, s42, s0
	s_addc_u32 s1, s43, 0
	s_and_b64 s[18:19], s[16:17], exec
	s_mov_b32 s18, 0x28480000
	s_cselect_b32 s20, s18, 0x8080000
	s_cselect_b32 s18, -8, -4
	s_add_i32 s18, s18, s59
	s_lshl_b32 s22, s18, 8
	v_or_b32_e32 v166, s22, v136
	s_mov_b64 s[18:19], -1
	s_cmpk_lt_i32 s57, 0x80
	v_ashrrev_i32_e32 v167, 31, v166
	s_cbranch_scc1 .LBB0_223
	s_and_b64 s[16:17], s[16:17], exec
	s_mov_b32 s16, 0x48680000
	s_cselect_b32 s16, s16, 0x28280000
	v_readlane_b32 s17, v255, 34
	s_add_u32 s16, s17, s16
	v_readlane_b32 s17, v255, 36
	s_addc_u32 s17, s17, 0
	v_lshl_add_u64 v[168:169], v[166:167], 1, s[0:1]
	v_lshl_add_u64 v[170:171], v[166:167], 2, s[16:17]
	v_lshl_add_u64 v[172:173], v[168:169], 0, v[138:139]
	v_cvt_pk_bf16_f32 v176, v124, v125
	v_cvt_pk_bf16_f32 v177, v126, v127
	v_lshl_add_u64 v[174:175], v[170:171], 0, v[140:141]
	global_store_dwordx2 v[172:173], v[176:177], off
	global_store_dwordx4 v[174:175], v[124:127], off nt
	v_cvt_pk_bf16_f32 v176, v120, v121
	v_cvt_pk_bf16_f32 v177, v122, v123
	global_store_dwordx2 v[172:173], v[176:177], off offset:32
	global_store_dwordx4 v[174:175], v[120:123], off offset:64 nt
	v_cvt_pk_bf16_f32 v176, v116, v117
	v_cvt_pk_bf16_f32 v177, v118, v119
	global_store_dwordx2 v[172:173], v[176:177], off offset:256
	global_store_dwordx4 v[174:175], v[116:119], off offset:512 nt
	v_cvt_pk_bf16_f32 v176, v112, v113
	v_cvt_pk_bf16_f32 v177, v114, v115
	global_store_dwordx2 v[172:173], v[176:177], off offset:288
	global_store_dwordx4 v[174:175], v[112:115], off offset:576 nt
	v_lshl_add_u64 v[172:173], v[168:169], 0, v[142:143]
	v_cvt_pk_bf16_f32 v176, v108, v109
	v_cvt_pk_bf16_f32 v177, v110, v111
	v_lshl_add_u64 v[174:175], v[170:171], 0, v[144:145]
	global_store_dwordx2 v[172:173], v[176:177], off
	global_store_dwordx4 v[174:175], v[108:111], off nt
	v_cvt_pk_bf16_f32 v176, v104, v105
	v_cvt_pk_bf16_f32 v177, v106, v107
	global_store_dwordx2 v[172:173], v[176:177], off offset:32
	global_store_dwordx4 v[174:175], v[104:107], off offset:64 nt
	v_cvt_pk_bf16_f32 v176, v100, v101
	v_cvt_pk_bf16_f32 v177, v102, v103
	global_store_dwordx2 v[172:173], v[176:177], off offset:256
	global_store_dwordx4 v[174:175], v[100:103], off offset:512 nt
	v_cvt_pk_bf16_f32 v176, v96, v97
	v_cvt_pk_bf16_f32 v177, v98, v99
	global_store_dwordx2 v[172:173], v[176:177], off offset:288
	global_store_dwordx4 v[174:175], v[96:99], off offset:576 nt
	v_lshl_add_u64 v[172:173], v[168:169], 0, v[146:147]
	v_cvt_pk_bf16_f32 v176, v92, v93
	v_cvt_pk_bf16_f32 v177, v94, v95
	v_lshl_add_u64 v[174:175], v[170:171], 0, v[148:149]
	global_store_dwordx2 v[172:173], v[176:177], off
	global_store_dwordx4 v[174:175], v[92:95], off nt
	v_cvt_pk_bf16_f32 v176, v88, v89
	v_cvt_pk_bf16_f32 v177, v90, v91
	global_store_dwordx2 v[172:173], v[176:177], off offset:32
	global_store_dwordx4 v[174:175], v[88:91], off offset:64 nt
	v_cvt_pk_bf16_f32 v176, v84, v85
	v_cvt_pk_bf16_f32 v177, v86, v87
	global_store_dwordx2 v[172:173], v[176:177], off offset:256
	global_store_dwordx4 v[174:175], v[84:87], off offset:512 nt
	v_cvt_pk_bf16_f32 v176, v80, v81
	v_cvt_pk_bf16_f32 v177, v82, v83
	global_store_dwordx2 v[172:173], v[176:177], off offset:288
	global_store_dwordx4 v[174:175], v[80:83], off offset:576 nt
	v_lshl_add_u64 v[168:169], v[168:169], 0, v[150:151]
	v_cvt_pk_bf16_f32 v172, v76, v77
	v_cvt_pk_bf16_f32 v173, v78, v79
	v_lshl_add_u64 v[170:171], v[170:171], 0, v[152:153]
	global_store_dwordx2 v[168:169], v[172:173], off
	global_store_dwordx4 v[170:171], v[76:79], off nt
	v_cvt_pk_bf16_f32 v172, v72, v73
	v_cvt_pk_bf16_f32 v173, v74, v75
	global_store_dwordx2 v[168:169], v[172:173], off offset:32
	global_store_dwordx4 v[170:171], v[72:75], off offset:64 nt
	v_cvt_pk_bf16_f32 v172, v68, v69
	v_cvt_pk_bf16_f32 v173, v70, v71
	global_store_dwordx2 v[168:169], v[172:173], off offset:256
	global_store_dwordx4 v[170:171], v[68:71], off offset:512 nt
	v_cvt_pk_bf16_f32 v172, v64, v65
	v_cvt_pk_bf16_f32 v173, v66, v67
	s_and_b64 vcc, exec, s[60:61]
	global_store_dwordx2 v[168:169], v[172:173], off offset:288
	global_store_dwordx4 v[170:171], v[64:67], off offset:576 nt
	s_cbranch_vccz .LBB0_222
	v_mov_b32_e32 v165, v129
	v_lshl_add_u64 v[168:169], s[0:1], 0, v[164:165]
	v_lshl_add_u64 v[168:169], v[166:167], 1, v[168:169]
	s_mov_b64 s[16:17], 0x5300000
	v_lshl_add_u64 v[170:171], v[168:169], 0, s[16:17]
	v_add_co_u32_e32 v168, vcc, 0x5300000, v168
	v_cvt_pk_bf16_f32 v172, v60, v61
	v_cvt_pk_bf16_f32 v173, v62, v63
	s_mov_b64 s[16:17], 0
	s_nop 0
	v_addc_co_u32_e32 v169, vcc, 0, v169, vcc
	global_store_dwordx2 v[168:169], v[172:173], off
	v_cvt_pk_bf16_f32 v168, v56, v57
	v_cvt_pk_bf16_f32 v169, v58, v59
	global_store_dwordx2 v[170:171], v[168:169], off offset:32
	v_cvt_pk_bf16_f32 v168, v52, v53
	v_cvt_pk_bf16_f32 v169, v54, v55
	global_store_dwordx2 v[170:171], v[168:169], off offset:256
	v_cvt_pk_bf16_f32 v168, v48, v49
	v_cvt_pk_bf16_f32 v169, v50, v51
	global_store_dwordx2 v[170:171], v[168:169], off offset:288
	v_add_u32_e32 v168, s22, v136
	v_ashrrev_i32_e32 v169, 31, v168
	v_lshl_add_u64 v[168:169], v[168:169], 2, s[20:21]
	v_lshl_add_u64 v[168:169], v[160:161], 0, v[168:169]
.LBB0_221:
	v_lshl_add_u64 v[170:171], v[168:169], 0, s[16:17]
	s_add_u32 s16, s16, 0x1010000
	s_addc_u32 s17, s17, 0
	s_cmp_eq_u32 s16, 0x8080000
	global_store_dwordx4 v[170:171], v[60:63], off offset:-512 nt
	global_store_dwordx4 v[170:171], v[56:59], off offset:-448 nt
	global_store_dwordx4 v[170:171], v[52:55], off nt
	global_store_dwordx4 v[170:171], v[48:51], off offset:64 nt
	s_cbranch_scc0 .LBB0_221

; __device__ __forceinline__ u32x2 pk4(f32x4 v) { u32x2 w; w.x = pk2(v[0], v[1]); w.y = pk2(v[2], v[3]); return w; }
;     __device__ __forceinline__ void operator()(const f32x4 (&acc)[2][2][4][2], const Unit& u, int wr, int wc, int fr, int fq) const {
;     ...
;             if (pm < 128) {
;                 const int b1 = (pm >> 4) + 1;
; #pragma unroll
;                 for (int ai = 0; ai < 2; ++ai)
; #pragma unroll
;                     for (int m = 0; m < 4; ++m) { const int r = pm * 256 + ai * 128 + m * 16 + lr0;
;                         bf16_t* kp = KV + (size_t)(r + 64 * b1) * 1024 + c0; float* fp = op + (size_t)(r + 16 * b1) * 1024 + c0;
; #pragma unroll
;                         for (int bj = 0; bj < 2; ++bj)
; #pragma unroll
;                             for (int n = 0; n < 2; ++n) { const f32x4 v = acc[ai][bj][m][n]; *(u32x2*)(kp + bj * 128 + n * 16) = pk4(v); *(f32x4*)(fp + bj * 128 + n * 16) = v; } }
.LBB0_223:
	s_andn2_b64 vcc, exec, s[18:19]
	s_cbranch_vccnz .LBB0_225
	s_add_u32 s18, s77, s20
	s_addc_u32 s19, s78, 0
	s_ashr_i32 s16, s57, 4
	s_add_i32 s17, s16, 1
	v_lshl_add_u32 v128, s57, 8, v134
	s_lshl_b32 s16, s17, 6
	v_lshl_add_u64 v[168:169], v[166:167], 1, s[0:1]
	v_add_u32_e32 v170, s16, v128
	s_mul_i32 s0, s17, 0xffffffd0
	v_ashrrev_i32_e32 v171, 31, v170
	v_add_u32_e32 v174, s0, v170
	v_lshlrev_b64 v[172:173], 11, v[170:171]
	v_ashrrev_i32_e32 v175, 31, v174
	v_lshl_add_u64 v[166:167], v[166:167], 2, s[18:19]
	v_lshl_add_u64 v[172:173], v[168:169], 0, v[172:173]
	v_lshlrev_b64 v[174:175], 12, v[174:175]
	v_cvt_pk_bf16_f32 v176, v124, v125
	v_cvt_pk_bf16_f32 v177, v126, v127
	v_lshl_add_u64 v[174:175], v[166:167], 0, v[174:175]
	global_store_dwordx2 v[172:173], v[176:177], off
	global_store_dwordx4 v[174:175], v[124:127], off nt
	v_cvt_pk_bf16_f32 v176, v120, v121
	v_cvt_pk_bf16_f32 v177, v122, v123
	global_store_dwordx2 v[172:173], v[176:177], off offset:32
	global_store_dwordx4 v[174:175], v[120:123], off offset:64 nt
	v_cvt_pk_bf16_f32 v176, v116, v117
	v_cvt_pk_bf16_f32 v177, v118, v119
	global_store_dwordx2 v[172:173], v[176:177], off offset:256
	global_store_dwordx4 v[174:175], v[116:119], off offset:512 nt
	v_cvt_pk_bf16_f32 v176, v112, v113
	v_cvt_pk_bf16_f32 v177, v114, v115
	s_and_b32 s18, s57, -16
	global_store_dwordx2 v[172:173], v[176:177], off offset:288
	global_store_dwordx4 v[174:175], v[112:115], off offset:576 nt
	v_or_b32_e32 v172, 16, v170
	s_add_i32 s1, s18, 32
	v_ashrrev_i32_e32 v173, 31, v172
	v_add_u32_e32 v174, s1, v128
	v_lshlrev_b64 v[172:173], 11, v[172:173]
	v_ashrrev_i32_e32 v175, 31, v174
	v_lshl_add_u64 v[172:173], v[168:169], 0, v[172:173]
	v_lshlrev_b64 v[174:175], 12, v[174:175]
	v_cvt_pk_bf16_f32 v176, v108, v109
	v_cvt_pk_bf16_f32 v177, v110, v111
	v_lshl_add_u64 v[174:175], v[166:167], 0, v[174:175]
	global_store_dwordx2 v[172:173], v[176:177], off
	global_store_dwordx4 v[174:175], v[108:111], off nt
	v_cvt_pk_bf16_f32 v176, v104, v105
	v_cvt_pk_bf16_f32 v177, v106, v107
	global_store_dwordx2 v[172:173], v[176:177], off offset:32
	global_store_dwordx4 v[174:175], v[104:107], off offset:64 nt
	v_cvt_pk_bf16_f32 v176, v100, v101
	v_cvt_pk_bf16_f32 v177, v102, v103
	global_store_dwordx2 v[172:173], v[176:177], off offset:256
	global_store_dwordx4 v[174:175], v[100:103], off offset:512 nt
	v_cvt_pk_bf16_f32 v176, v96, v97
	v_cvt_pk_bf16_f32 v177, v98, v99
	global_store_dwordx2 v[172:173], v[176:177], off offset:288
	global_store_dwordx4 v[174:175], v[96:99], off offset:576 nt
	v_or_b32_e32 v172, 32, v170
	s_add_i32 s17, s18, 48
	v_ashrrev_i32_e32 v173, 31, v172
	v_add_u32_e32 v174, s17, v128
	v_lshlrev_b64 v[172:173], 11, v[172:173]
	v_ashrrev_i32_e32 v175, 31, v174
	v_lshl_add_u64 v[172:173], v[168:169], 0, v[172:173]
	v_lshlrev_b64 v[174:175], 12, v[174:175]
	v_cvt_pk_bf16_f32 v176, v92, v93
	v_cvt_pk_bf16_f32 v177, v94, v95
	v_lshl_add_u64 v[174:175], v[166:167], 0, v[174:175]
	global_store_dwordx2 v[172:173], v[176:177], off
	global_store_dwordx4 v[174:175], v[92:95], off nt
	v_cvt_pk_bf16_f32 v176, v88, v89
	v_cvt_pk_bf16_f32 v177, v90, v91
	global_store_dwordx2 v[172:173], v[176:177], off offset:32
	global_store_dwordx4 v[174:175], v[88:91], off offset:64 nt
	v_cvt_pk_bf16_f32 v176, v84, v85
	v_cvt_pk_bf16_f32 v177, v86, v87
	global_store_dwordx2 v[172:173], v[176:177], off offset:256
	global_store_dwordx4 v[174:175], v[84:87], off offset:512 nt
	v_cvt_pk_bf16_f32 v176, v80, v81
	v_cvt_pk_bf16_f32 v177, v82, v83
	global_store_dwordx2 v[172:173], v[176:177], off offset:288
	global_store_dwordx4 v[174:175], v[80:83], off offset:576 nt
	v_or_b32_e32 v172, 48, v170
	s_add_i32 s18, s18, 64
	v_ashrrev_i32_e32 v173, 31, v172
	v_add_u32_e32 v174, s18, v128
	v_lshlrev_b64 v[172:173], 11, v[172:173]
	v_ashrrev_i32_e32 v175, 31, v174
	v_lshl_add_u64 v[172:173], v[168:169], 0, v[172:173]
	v_lshlrev_b64 v[174:175], 12, v[174:175]
	v_cvt_pk_bf16_f32 v176, v76, v77
	v_cvt_pk_bf16_f32 v177, v78, v79
	v_lshl_add_u64 v[174:175], v[166:167], 0, v[174:175]
	global_store_dwordx2 v[172:173], v[176:177], off
	global_store_dwordx4 v[174:175], v[76:79], off nt
	v_cvt_pk_bf16_f32 v176, v72, v73
	v_cvt_pk_bf16_f32 v177, v74, v75
	global_store_dwordx2 v[172:173], v[176:177], off offset:32
	global_store_dwordx4 v[174:175], v[72:75], off offset:64 nt
	v_cvt_pk_bf16_f32 v176, v68, v69
	v_cvt_pk_bf16_f32 v177, v70, v71
	global_store_dwordx2 v[172:173], v[176:177], off offset:256
; __device__ __forceinline__ u32x2 pk4(f32x4 v) { u32x2 w; w.x = pk2(v[0], v[1]); w.y = pk2(v[2], v[3]); return w; }
;     __device__ __forceinline__ void operator()(const f32x4 (&acc)[2][2][4][2], const Unit& u, int wr, int wc, int fr, int fq) const {
;     ...
;                 for (int ai = 0; ai < 2; ++ai)
; #pragma unroll
;                     for (int m = 0; m < 4; ++m) { const int r = pm * 256 + ai * 128 + m * 16 + lr0;
;                         bf16_t* kp = KV + (size_t)(r + 64 * b1) * 1024 + c0; float* fp = op + (size_t)(r + 16 * b1) * 1024 + c0;
; #pragma unroll
;                         for (int bj = 0; bj < 2; ++bj)
; #pragma unroll
;                             for (int n = 0; n < 2; ++n) { const f32x4 v = acc[ai][bj][m][n]; *(u32x2*)(kp + bj * 128 + n * 16) = pk4(v); *(f32x4*)(fp + bj * 128 + n * 16) = v; } }
	global_store_dwordx4 v[174:175], v[68:71], off offset:512 nt
	v_cvt_pk_bf16_f32 v176, v64, v65
	v_cvt_pk_bf16_f32 v177, v66, v67
	v_add_u32_e32 v128, 0x80, v128
	global_store_dwordx2 v[172:173], v[176:177], off offset:288
	global_store_dwordx4 v[174:175], v[64:67], off offset:576 nt
	v_add_u32_e32 v172, s16, v128
	v_ashrrev_i32_e32 v173, 31, v172
	v_lshlrev_b64 v[174:175], 11, v[172:173]
	v_add_u32_e32 v172, s0, v172
	v_ashrrev_i32_e32 v173, 31, v172
	v_lshl_add_u64 v[174:175], v[168:169], 0, v[174:175]
	v_lshlrev_b64 v[172:173], 12, v[172:173]
	v_cvt_pk_bf16_f32 v176, v60, v61
	v_cvt_pk_bf16_f32 v177, v62, v63
	v_lshl_add_u64 v[172:173], v[166:167], 0, v[172:173]
	global_store_dwordx2 v[174:175], v[176:177], off
	global_store_dwordx4 v[172:173], v[60:63], off nt
	v_cvt_pk_bf16_f32 v176, v56, v57
	v_cvt_pk_bf16_f32 v177, v58, v59
	global_store_dwordx2 v[174:175], v[176:177], off offset:32
	global_store_dwordx4 v[172:173], v[56:59], off offset:64 nt
	v_cvt_pk_bf16_f32 v176, v52, v53
	v_cvt_pk_bf16_f32 v177, v54, v55
	global_store_dwordx2 v[174:175], v[176:177], off offset:256
	global_store_dwordx4 v[172:173], v[52:55], off offset:512 nt
	v_cvt_pk_bf16_f32 v176, v48, v49
	v_cvt_pk_bf16_f32 v177, v50, v51
	global_store_dwordx2 v[174:175], v[176:177], off offset:288
	global_store_dwordx4 v[172:173], v[48:51], off offset:576 nt
	v_add_u32_e32 v172, 0x90, v170
	v_ashrrev_i32_e32 v173, 31, v172
	v_add_u32_e32 v174, s1, v128
	v_lshlrev_b64 v[172:173], 11, v[172:173]
	v_ashrrev_i32_e32 v175, 31, v174
	v_lshl_add_u64 v[172:173], v[168:169], 0, v[172:173]
	v_lshlrev_b64 v[174:175], 12, v[174:175]
	v_cvt_pk_bf16_f32 v176, v44, v45
	v_cvt_pk_bf16_f32 v177, v46, v47
	v_lshl_add_u64 v[174:175], v[166:167], 0, v[174:175]
	global_store_dwordx2 v[172:173], v[176:177], off
	global_store_dwordx4 v[174:175], v[44:47], off nt
	v_cvt_pk_bf16_f32 v176, v40, v41
	v_cvt_pk_bf16_f32 v177, v42, v43
	global_store_dwordx2 v[172:173], v[176:177], off offset:32
	global_store_dwordx4 v[174:175], v[40:43], off offset:64 nt
	v_cvt_pk_bf16_f32 v176, v36, v37
	v_cvt_pk_bf16_f32 v177, v38, v39
	global_store_dwordx2 v[172:173], v[176:177], off offset:256
	global_store_dwordx4 v[174:175], v[36:39], off offset:512 nt
	v_cvt_pk_bf16_f32 v176, v32, v33
	v_cvt_pk_bf16_f32 v177, v34, v35
	global_store_dwordx2 v[172:173], v[176:177], off offset:288
	global_store_dwordx4 v[174:175], v[32:35], off offset:576 nt
	v_add_u32_e32 v172, 0xa0, v170
	v_ashrrev_i32_e32 v173, 31, v172
	v_add_u32_e32 v174, s17, v128
	v_add_u32_e32 v170, 0xb0, v170
	v_lshlrev_b64 v[172:173], 11, v[172:173]
	v_ashrrev_i32_e32 v175, 31, v174
	v_ashrrev_i32_e32 v171, 31, v170
	v_lshl_add_u64 v[172:173], v[168:169], 0, v[172:173]
	v_lshlrev_b64 v[174:175], 12, v[174:175]
	v_cvt_pk_bf16_f32 v176, v28, v29
	v_cvt_pk_bf16_f32 v177, v30, v31
	v_lshlrev_b64 v[170:171], 11, v[170:171]
	v_lshl_add_u64 v[174:175], v[166:167], 0, v[174:175]
	global_store_dwordx2 v[172:173], v[176:177], off
	global_store_dwordx4 v[174:175], v[28:31], off nt
	v_cvt_pk_bf16_f32 v176, v24, v25
	v_cvt_pk_bf16_f32 v177, v26, v27
	v_lshl_add_u64 v[168:169], v[168:169], 0, v[170:171]
	v_add_u32_e32 v170, s18, v128
	global_store_dwordx2 v[172:173], v[176:177], off offset:32
	global_store_dwordx4 v[174:175], v[24:27], off offset:64 nt
	v_cvt_pk_bf16_f32 v176, v20, v21
	v_cvt_pk_bf16_f32 v177, v22, v23
	v_ashrrev_i32_e32 v171, 31, v170
	global_store_dwordx2 v[172:173], v[176:177], off offset:256
	global_store_dwordx4 v[174:175], v[20:23], off offset:512 nt
	v_cvt_pk_bf16_f32 v176, v16, v17
	v_cvt_pk_bf16_f32 v177, v18, v19
	v_lshlrev_b64 v[170:171], 12, v[170:171]
	global_store_dwordx2 v[172:173], v[176:177], off offset:288
	global_store_dwordx4 v[174:175], v[16:19], off offset:576 nt
	v_lshl_add_u64 v[166:167], v[166:167], 0, v[170:171]
	v_cvt_pk_bf16_f32 v170, v12, v13
	v_cvt_pk_bf16_f32 v171, v14, v15
	global_store_dwordx2 v[168:169], v[170:171], off
	global_store_dwordx4 v[166:167], v[12:15], off nt
	v_cvt_pk_bf16_f32 v170, v8, v9
	v_cvt_pk_bf16_f32 v171, v10, v11
	global_store_dwordx2 v[168:169], v[170:171], off offset:32
	global_store_dwordx4 v[166:167], v[8:11], off offset:64 nt
	v_cvt_pk_bf16_f32 v170, v4, v5
	v_cvt_pk_bf16_f32 v171, v6, v7
	global_store_dwordx2 v[168:169], v[170:171], off offset:256
	global_store_dwordx4 v[166:167], v[4:7], off offset:512 nt
	v_cvt_pk_bf16_f32 v170, v0, v1
	v_cvt_pk_bf16_f32 v171, v2, v3
	global_store_dwordx2 v[168:169], v[170:171], off offset:288
	global_store_dwordx4 v[166:167], v[0:3], off offset:576 nt
